# x and mem_w_q f32->bf16 conversion batched (8/4 chunks in flight); S5 scans 4-FMA form; DPP quad reductions in NSA importance and top-k
# speedup vs baseline: 1.0283x; 1.0156x over previous
.LBB0_123:
	s_mov_b32 s28, s92
	s_load_dwordx2 s[38:39], s[90:91], 0xb0
	s_waitcnt lgkmcnt(0)
	s_load_dwordx2 s[4:5], s[90:91], 0xf0
	s_waitcnt lgkmcnt(0)
	s_lshl_b32 s28, s28, 9
	s_add_i32 s28, s28, s83
	v_mbcnt_lo_u32_b32 v2, -1, 0
	v_mbcnt_hi_u32_b32 v2, -1, v2
	s_lshl_b64 s[30:31], s[12:13], 22
	v_add_u32_e32 v10, s28, v2
	v_ashrrev_i32_e32 v11, 31, v10
	v_lshlrev_b64 v[18:19], 3, v[10:11]
	s_lshl_b32 s43, s12, 23
	v_cmp_gt_u64_e32 vcc, s[14:15], v[18:19]
	s_and_saveexec_b64 s[28:29], vcc
	s_cbranch_execz .LBB0_128
	s_lshl_b64 s[36:37], s[30:31], 2
	s_add_u32 s36, s38, s36
	s_addc_u32 s37, s39, s37
	v_lshl_add_u64 v[2:3], v[18:19], 2, s[36:37]
	global_load_dwordx4 v[6:9], v[2:3], off
	s_nop 0
	global_load_dwordx4 v[2:5], v[2:3], off offset:16
	s_add_u32 s44, s38, s8
	s_addc_u32 s45, s39, s9
	s_lshl_b64 s[38:39], s[12:13], 24
	s_add_u32 s38, s44, s38
	s_addc_u32 s39, s45, s39
	s_add_u32 s4, s4, s43
	s_addc_u32 s5, s5, 0
	s_cmp_eq_u32 s6, 0x100000
	s_cbranch_scc0 .Lcvq_slow
	s_cmp_eq_u32 s7, 0
	s_cbranch_scc0 .Lcvq_slow
	v_lshl_add_u64 v[102:103], v[18:19], 2, s[36:37]
	v_lshl_add_u64 v[104:105], v[10:11], 4, s[4:5]
	v_lshl_add_u64 v[104:105], v[104:105], 0, s[16:17]
	global_load_dwordx4 v[110:113], v[102:103], off
	global_load_dwordx4 v[114:117], v[102:103], off offset:16
	v_lshl_add_u64 v[102:103], v[102:103], 0, s[8:9]
	global_load_dwordx4 v[118:121], v[102:103], off
	global_load_dwordx4 v[122:125], v[102:103], off offset:16
	v_lshl_add_u64 v[102:103], v[102:103], 0, s[8:9]
	global_load_dwordx4 v[126:129], v[102:103], off
	global_load_dwordx4 v[130:133], v[102:103], off offset:16
	v_lshl_add_u64 v[102:103], v[102:103], 0, s[8:9]
	global_load_dwordx4 v[134:137], v[102:103], off
	global_load_dwordx4 v[138:141], v[102:103], off offset:16
	v_lshl_add_u64 v[102:103], v[102:103], 0, s[8:9]
	s_waitcnt vmcnt(6)
	v_cvt_pk_bf16_f32 v142, v110, v111
	v_cvt_pk_bf16_f32 v143, v112, v113
	v_cvt_pk_bf16_f32 v144, v114, v115
	v_cvt_pk_bf16_f32 v145, v116, v117
	global_store_dwordx4 v[104:105], v[142:145], off
	v_lshl_add_u64 v[104:105], v[104:105], 0, s[10:11]
	s_waitcnt vmcnt(5)
	v_cvt_pk_bf16_f32 v146, v118, v119
	v_cvt_pk_bf16_f32 v147, v120, v121
	v_cvt_pk_bf16_f32 v148, v122, v123
	v_cvt_pk_bf16_f32 v149, v124, v125
	global_store_dwordx4 v[104:105], v[146:149], off
	v_lshl_add_u64 v[104:105], v[104:105], 0, s[10:11]
	s_waitcnt vmcnt(4)
	v_cvt_pk_bf16_f32 v142, v126, v127
	v_cvt_pk_bf16_f32 v143, v128, v129
	v_cvt_pk_bf16_f32 v144, v130, v131
	v_cvt_pk_bf16_f32 v145, v132, v133
	global_store_dwordx4 v[104:105], v[142:145], off
	v_lshl_add_u64 v[104:105], v[104:105], 0, s[10:11]
	s_waitcnt vmcnt(3)
	v_cvt_pk_bf16_f32 v146, v134, v135
	v_cvt_pk_bf16_f32 v147, v136, v137
	v_cvt_pk_bf16_f32 v148, v138, v139
	v_cvt_pk_bf16_f32 v149, v140, v141
	global_store_dwordx4 v[104:105], v[146:149], off
	v_lshl_add_u64 v[104:105], v[104:105], 0, s[10:11]
	s_branch .LBB0_128
.Lcvq_slow:
	v_lshlrev_b64 v[12:13], 5, v[10:11]
	v_lshl_add_u64 v[10:11], v[10:11], 4, s[4:5]
	v_lshl_add_u64 v[20:21], s[38:39], 0, v[12:13]
	v_lshl_add_u64 v[22:23], v[10:11], 0, s[16:17]
	s_mov_b64 s[36:37], 0
	s_waitcnt vmcnt(0) lgkmcnt(0)
	v_mov_b64_e32 v[12:13], v[8:9]
	v_mov_b64_e32 v[16:17], v[4:5]
	v_mov_b64_e32 v[10:11], v[6:7]
	v_mov_b64_e32 v[14:15], v[2:3]
	s_branch .LBB0_126

.LBB0_204:
	s_mov_b32 s12, s92
	s_load_dwordx2 s[4:5], s[90:91], 0
	s_waitcnt lgkmcnt(0)
	s_load_dwordx2 s[16:17], s[90:91], 0xf0
	s_waitcnt lgkmcnt(0)
	s_lshl_b32 s12, s12, 9
	s_add_i32 s12, s12, s83
	v_mbcnt_lo_u32_b32 v2, -1, 0
	v_mbcnt_hi_u32_b32 v2, -1, v2
	s_nop 0
	v_add_u32_e32 v10, s12, v2
	v_ashrrev_i32_e32 v11, 31, v10
	v_lshlrev_b64 v[18:19], 3, v[10:11]
	s_mov_b64 s[12:13], 0x2000000
	v_cmp_gt_u64_e32 vcc, s[12:13], v[18:19]
	s_and_saveexec_b64 s[14:15], vcc
	s_cbranch_execz .LBB0_209
	s_cmp_eq_u32 s6, 0x100000
	s_cbranch_scc0 .Lcvx_slow
	s_cmp_eq_u32 s7, 0
	s_cbranch_scc0 .Lcvx_slow
	v_lshl_add_u64 v[12:13], v[18:19], 2, s[4:5]
	v_lshl_add_u64 v[20:21], v[10:11], 4, s[16:17]
	s_mov_b64 s[20:21], 0x10000000
	v_lshl_add_u64 v[20:21], v[20:21], 0, s[20:21]
	s_mov_b32 s4, 0
.Lcvx_loop:
	v_mov_b64_e32 v[24:25], v[12:13]
	global_load_dwordx4 v[30:33], v[24:25], off
	global_load_dwordx4 v[34:37], v[24:25], off offset:16
	v_lshl_add_u64 v[24:25], v[24:25], 0, s[8:9]
	global_load_dwordx4 v[38:41], v[24:25], off
	global_load_dwordx4 v[42:45], v[24:25], off offset:16
	v_lshl_add_u64 v[24:25], v[24:25], 0, s[8:9]
	global_load_dwordx4 v[46:49], v[24:25], off
	global_load_dwordx4 v[50:53], v[24:25], off offset:16
	v_lshl_add_u64 v[24:25], v[24:25], 0, s[8:9]
	global_load_dwordx4 v[54:57], v[24:25], off
	global_load_dwordx4 v[58:61], v[24:25], off offset:16
	v_lshl_add_u64 v[24:25], v[24:25], 0, s[8:9]
	global_load_dwordx4 v[62:65], v[24:25], off
	global_load_dwordx4 v[66:69], v[24:25], off offset:16
	v_lshl_add_u64 v[24:25], v[24:25], 0, s[8:9]
	global_load_dwordx4 v[70:73], v[24:25], off
	global_load_dwordx4 v[74:77], v[24:25], off offset:16
	v_lshl_add_u64 v[24:25], v[24:25], 0, s[8:9]
	global_load_dwordx4 v[78:81], v[24:25], off
	global_load_dwordx4 v[82:85], v[24:25], off offset:16
	v_lshl_add_u64 v[24:25], v[24:25], 0, s[8:9]
	global_load_dwordx4 v[86:89], v[24:25], off
	global_load_dwordx4 v[90:93], v[24:25], off offset:16
	v_lshl_add_u64 v[24:25], v[24:25], 0, s[8:9]
	v_mov_b64_e32 v[12:13], v[24:25]
	s_waitcnt vmcnt(14)
	v_cvt_pk_bf16_f32 v94, v30, v31
	v_cvt_pk_bf16_f32 v95, v32, v33
	v_cvt_pk_bf16_f32 v96, v34, v35
	v_cvt_pk_bf16_f32 v97, v36, v37
	global_store_dwordx4 v[20:21], v[94:97], off
	v_lshl_add_u64 v[20:21], v[20:21], 0, s[10:11]
	s_waitcnt vmcnt(13)
	v_cvt_pk_bf16_f32 v98, v38, v39
	v_cvt_pk_bf16_f32 v99, v40, v41
	v_cvt_pk_bf16_f32 v100, v42, v43
	v_cvt_pk_bf16_f32 v101, v44, v45
	global_store_dwordx4 v[20:21], v[98:101], off
	v_lshl_add_u64 v[20:21], v[20:21], 0, s[10:11]
	s_waitcnt vmcnt(12)
	v_cvt_pk_bf16_f32 v94, v46, v47
	v_cvt_pk_bf16_f32 v95, v48, v49
	v_cvt_pk_bf16_f32 v96, v50, v51
	v_cvt_pk_bf16_f32 v97, v52, v53
	global_store_dwordx4 v[20:21], v[94:97], off
	v_lshl_add_u64 v[20:21], v[20:21], 0, s[10:11]
	s_waitcnt vmcnt(11)
	v_cvt_pk_bf16_f32 v98, v54, v55
	v_cvt_pk_bf16_f32 v99, v56, v57
	v_cvt_pk_bf16_f32 v100, v58, v59
	v_cvt_pk_bf16_f32 v101, v60, v61
	global_store_dwordx4 v[20:21], v[98:101], off
	v_lshl_add_u64 v[20:21], v[20:21], 0, s[10:11]
	s_waitcnt vmcnt(10)
	v_cvt_pk_bf16_f32 v94, v62, v63
	v_cvt_pk_bf16_f32 v95, v64, v65
	v_cvt_pk_bf16_f32 v96, v66, v67
	v_cvt_pk_bf16_f32 v97, v68, v69
	global_store_dwordx4 v[20:21], v[94:97], off
	v_lshl_add_u64 v[20:21], v[20:21], 0, s[10:11]
	s_waitcnt vmcnt(9)
	v_cvt_pk_bf16_f32 v98, v70, v71
	v_cvt_pk_bf16_f32 v99, v72, v73
	v_cvt_pk_bf16_f32 v100, v74, v75
	v_cvt_pk_bf16_f32 v101, v76, v77
	global_store_dwordx4 v[20:21], v[98:101], off
	v_lshl_add_u64 v[20:21], v[20:21], 0, s[10:11]
	s_waitcnt vmcnt(8)
	v_cvt_pk_bf16_f32 v94, v78, v79
	v_cvt_pk_bf16_f32 v95, v80, v81
	v_cvt_pk_bf16_f32 v96, v82, v83
	v_cvt_pk_bf16_f32 v97, v84, v85
	global_store_dwordx4 v[20:21], v[94:97], off
	v_lshl_add_u64 v[20:21], v[20:21], 0, s[10:11]
	s_waitcnt vmcnt(7)
	v_cvt_pk_bf16_f32 v98, v86, v87
	v_cvt_pk_bf16_f32 v99, v88, v89
	v_cvt_pk_bf16_f32 v100, v90, v91
	v_cvt_pk_bf16_f32 v101, v92, v93
	global_store_dwordx4 v[20:21], v[98:101], off
	v_lshl_add_u64 v[20:21], v[20:21], 0, s[10:11]
	s_add_i32 s4, s4, 1
	s_cmp_lt_u32 s4, 4
	s_cbranch_scc1 .Lcvx_loop
	s_branch .LBB0_209
.Lcvx_slow:
	v_lshl_add_u64 v[12:13], v[18:19], 2, s[4:5]
	global_load_dwordx4 v[6:9], v[12:13], off
	global_load_dwordx4 v[2:5], v[12:13], off offset:16
	s_add_u32 s4, s4, s8
	v_lshlrev_b64 v[12:13], 5, v[10:11]
	v_lshl_add_u64 v[10:11], v[10:11], 4, s[16:17]
	s_mov_b64 s[20:21], 0x10000000
	s_addc_u32 s5, s5, s9
	v_lshl_add_u64 v[20:21], v[10:11], 0, s[20:21]
	v_lshl_add_u64 v[22:23], s[4:5], 0, v[12:13]
	s_mov_b64 s[16:17], 0
	s_mov_b64 s[18:19], 0x1ffffff
	s_waitcnt vmcnt(0) lgkmcnt(0)
	v_mov_b64_e32 v[12:13], v[8:9]
	v_mov_b64_e32 v[16:17], v[4:5]
	v_mov_b64_e32 v[10:11], v[6:7]
	v_mov_b64_e32 v[14:15], v[2:3]
	s_branch .LBB0_207

.LBB0_675:
	s_add_i32 s18, s18, 0
	v_add_u32_e32 v70, s18, v0
	v_add_u32_e32 v74, s18, v107
	ds_read_b128 v[66:69], v70
	ds_read_b128 v[70:73], v70 offset:8192
	ds_read_b128 v[196:199], v74
	ds_read_b128 v[200:203], v74 offset:8192
	v_add_u32_e32 v74, s18, v109
	ds_read_b128 v[204:207], v74
	ds_read_b128 v[208:211], v74 offset:8192
	s_waitcnt lgkmcnt(0)
	v_mfma_f32_32x32x16_bf16 v[82:97], v[66:69], v[140:143], 0
	v_mfma_f32_32x32x16_bf16 v[66:81], v[70:73], v[140:143], 0
	v_add_u32_e32 v216, s18, v110
	ds_read_b128 v[212:215], v216
	ds_read_b128 v[216:219], v216 offset:8192
	v_mfma_f32_32x32x16_bf16 v[82:97], v[196:199], v[136:139], v[82:97]
	v_mfma_f32_32x32x16_bf16 v[66:81], v[200:203], v[136:139], v[66:81]
	v_add_u32_e32 v200, s18, v111
	ds_read_b128 v[196:199], v200
	ds_read_b128 v[200:203], v200 offset:8192
	v_mfma_f32_32x32x16_bf16 v[82:97], v[204:207], v[132:135], v[82:97]
	v_mfma_f32_32x32x16_bf16 v[66:81], v[208:211], v[132:135], v[66:81]
	v_add_u32_e32 v208, s18, v144
	ds_read_b128 v[204:207], v208
	ds_read_b128 v[208:211], v208 offset:8192
	s_waitcnt lgkmcnt(0)
	v_mfma_f32_32x32x16_bf16 v[82:97], v[212:215], v[128:131], v[82:97]
	v_mfma_f32_32x32x16_bf16 v[66:81], v[216:219], v[128:131], v[66:81]
	v_add_u32_e32 v216, s18, v145
	ds_read_b128 v[212:215], v216
	ds_read_b128 v[216:219], v216 offset:8192
	v_mfma_f32_32x32x16_bf16 v[82:97], v[196:199], v[124:127], v[82:97]
	v_mfma_f32_32x32x16_bf16 v[66:81], v[200:203], v[124:127], v[66:81]
	v_add_u32_e32 v200, s18, v146
	ds_read_b128 v[196:199], v200
	ds_read_b128 v[200:203], v200 offset:8192
	v_mfma_f32_32x32x16_bf16 v[82:97], v[204:207], v[120:123], v[82:97]
	v_mfma_f32_32x32x16_bf16 v[66:81], v[208:211], v[120:123], v[66:81]
	s_waitcnt lgkmcnt(0)
	v_mfma_f32_32x32x16_bf16 v[82:97], v[212:215], v[116:119], v[82:97]
	v_mfma_f32_32x32x16_bf16 v[66:81], v[216:219], v[116:119], v[66:81]
	v_mfma_f32_32x32x16_bf16 v[82:97], v[196:199], v[112:115], v[82:97]
	v_mfma_f32_32x32x16_bf16 v[66:81], v[200:203], v[112:115], v[66:81]
	s_nop 10
	v_exp_f32_e32 v82, v82
	v_exp_f32_e32 v83, v83
	v_exp_f32_e32 v84, v84
	v_add_u32_e32 v196, s16, v187
	v_exp_f32_e32 v85, v85
	v_mul_f32_e32 v82, v106, v82
	v_cmp_le_i32_e32 vcc, v196, v100
	v_mul_f32_e32 v83, v106, v83
	v_add_u32_e32 v197, 2, v196
	v_cndmask_b32_e32 v82, 0, v82, vcc
	v_cmp_lt_i32_e32 vcc, v196, v100
	v_mul_f32_e32 v84, v106, v84
	v_mul_f32_e32 v85, v106, v85
	v_cndmask_b32_e32 v83, 0, v83, vcc
	v_cmp_le_i32_e32 vcc, v197, v100
	v_add_u32_e32 v197, 3, v196
	s_nop 0
	v_cndmask_b32_e32 v84, 0, v84, vcc
	v_cmp_le_i32_e32 vcc, v197, v100
	v_add_f32_e32 v197, v82, v83
	s_nop 0
	v_cndmask_b32_e32 v85, 0, v85, vcc
	v_add_f32_e32 v198, v84, v85
	v_add_f32_e32 v197, v197, v198
	s_nop 0
	s_nop 1
	v_add_f32_dpp v240, v197, v197 quad_perm:[1,0,3,2] row_mask:0xf bank_mask:0xf
	v_add_f32_dpp v241, v85, v85 quad_perm:[1,0,3,2] row_mask:0xf bank_mask:0xf
	s_nop 1
	v_add_f32_dpp v242, v240, v240 quad_perm:[2,3,0,1] row_mask:0xf bank_mask:0xf
	v_add_f32_dpp v243, v241, v241 quad_perm:[2,3,0,1] row_mask:0xf bank_mask:0xf
	v_add_u32_e32 v197, s16, v195
	s_and_saveexec_b64 s[8:9], s[4:5]
	s_cbranch_execz .LBB0_677
	v_add_u32_e32 v202, 0x10000, v197
	v_add_u32_e32 v203, 0x10004, v197
	ds_add_f32 v202, v242
	ds_add_f32 v203, v243
.LBB0_677:
	s_or_b64 exec, exec, s[8:9]
	v_exp_f32_e32 v86, v86
	v_exp_f32_e32 v87, v87
	v_exp_f32_e32 v88, v88
	v_add_u32_e32 v198, 8, v196
	v_exp_f32_e32 v89, v89
	v_mul_f32_e32 v86, v106, v86
	v_cmp_le_i32_e32 vcc, v198, v100
	v_add_u32_e32 v198, 9, v196
	v_mul_f32_e32 v87, v106, v87
	v_cndmask_b32_e32 v86, 0, v86, vcc
	v_cmp_le_i32_e32 vcc, v198, v100
	v_add_u32_e32 v198, 10, v196
	v_mul_f32_e32 v88, v106, v88
	v_cndmask_b32_e32 v87, 0, v87, vcc
	v_cmp_le_i32_e32 vcc, v198, v100
	v_add_u32_e32 v198, 11, v196
	v_mul_f32_e32 v89, v106, v89
	v_cndmask_b32_e32 v88, 0, v88, vcc
	v_cmp_le_i32_e32 vcc, v198, v100
	v_add_f32_e32 v198, v86, v87
	s_nop 0
	v_cndmask_b32_e32 v89, 0, v89, vcc
	s_waitcnt lgkmcnt(0)
	v_add_f32_e32 v199, v88, v89
	v_add_f32_e32 v198, v198, v199
	s_nop 0
	s_nop 1
	v_add_f32_dpp v240, v198, v198 quad_perm:[1,0,3,2] row_mask:0xf bank_mask:0xf
	v_add_f32_dpp v241, v89, v89 quad_perm:[1,0,3,2] row_mask:0xf bank_mask:0xf
	s_nop 1
	v_add_f32_dpp v242, v240, v240 quad_perm:[2,3,0,1] row_mask:0xf bank_mask:0xf
	v_add_f32_dpp v243, v241, v241 quad_perm:[2,3,0,1] row_mask:0xf bank_mask:0xf
	s_and_saveexec_b64 s[8:9], s[4:5]
	s_cbranch_execz .LBB0_679
	v_add_u32_e32 v202, 0x10008, v197
	v_add_u32_e32 v203, 0x1000c, v197
	ds_add_f32 v202, v242
	ds_add_f32 v203, v243
.LBB0_679:
	s_or_b64 exec, exec, s[8:9]
	v_exp_f32_e32 v90, v90
	v_exp_f32_e32 v91, v91
	v_exp_f32_e32 v92, v92
	v_add_u32_e32 v198, 16, v196
	v_exp_f32_e32 v93, v93
	v_mul_f32_e32 v90, v106, v90
	v_cmp_le_i32_e32 vcc, v198, v100
	v_add_u32_e32 v198, 17, v196
	v_mul_f32_e32 v91, v106, v91
	v_cndmask_b32_e32 v90, 0, v90, vcc
	v_cmp_le_i32_e32 vcc, v198, v100
	v_add_u32_e32 v198, 18, v196
	v_mul_f32_e32 v92, v106, v92
	v_cndmask_b32_e32 v91, 0, v91, vcc
	v_cmp_le_i32_e32 vcc, v198, v100
	v_add_u32_e32 v198, 19, v196
	v_mul_f32_e32 v93, v106, v93
	v_cndmask_b32_e32 v92, 0, v92, vcc
	v_cmp_le_i32_e32 vcc, v198, v100
	v_add_f32_e32 v198, v90, v91
	s_nop 0
	v_cndmask_b32_e32 v93, 0, v93, vcc
	s_waitcnt lgkmcnt(0)
	v_add_f32_e32 v199, v92, v93
	v_add_f32_e32 v198, v198, v199
	s_nop 0
	s_nop 1
	v_add_f32_dpp v240, v198, v198 quad_perm:[1,0,3,2] row_mask:0xf bank_mask:0xf
	v_add_f32_dpp v241, v93, v93 quad_perm:[1,0,3,2] row_mask:0xf bank_mask:0xf
	s_nop 1
	v_add_f32_dpp v242, v240, v240 quad_perm:[2,3,0,1] row_mask:0xf bank_mask:0xf
	v_add_f32_dpp v243, v241, v241 quad_perm:[2,3,0,1] row_mask:0xf bank_mask:0xf
	s_and_saveexec_b64 s[8:9], s[4:5]
	s_cbranch_execz .LBB0_681
	v_add_u32_e32 v202, 0x10010, v197
	v_add_u32_e32 v203, 0x10014, v197
	ds_add_f32 v202, v242
	ds_add_f32 v203, v243
.LBB0_681:
	s_or_b64 exec, exec, s[8:9]
	v_exp_f32_e32 v94, v94
	v_exp_f32_e32 v95, v95
	v_exp_f32_e32 v96, v96
	v_add_u32_e32 v198, 24, v196
	v_exp_f32_e32 v97, v97
	v_mul_f32_e32 v94, v106, v94
	v_cmp_le_i32_e32 vcc, v198, v100
	v_add_u32_e32 v198, 25, v196
	v_mul_f32_e32 v95, v106, v95
	v_cndmask_b32_e32 v94, 0, v94, vcc
	v_cmp_le_i32_e32 vcc, v198, v100
	v_add_u32_e32 v198, 26, v196
	v_mul_f32_e32 v96, v106, v96
	v_cndmask_b32_e32 v95, 0, v95, vcc
	v_cmp_le_i32_e32 vcc, v198, v100
	v_add_u32_e32 v198, 27, v196
	v_mul_f32_e32 v97, v106, v97
	v_cndmask_b32_e32 v96, 0, v96, vcc
	v_cmp_le_i32_e32 vcc, v198, v100
	v_add_f32_e32 v198, v94, v95
	s_nop 0
	v_cndmask_b32_e32 v97, 0, v97, vcc
	s_waitcnt lgkmcnt(0)
	v_add_f32_e32 v199, v96, v97
	v_add_f32_e32 v198, v198, v199
	s_nop 0
	s_nop 1
	v_add_f32_dpp v240, v198, v198 quad_perm:[1,0,3,2] row_mask:0xf bank_mask:0xf
	v_add_f32_dpp v241, v97, v97 quad_perm:[1,0,3,2] row_mask:0xf bank_mask:0xf
	s_nop 1
	v_add_f32_dpp v242, v240, v240 quad_perm:[2,3,0,1] row_mask:0xf bank_mask:0xf
	v_add_f32_dpp v243, v241, v241 quad_perm:[2,3,0,1] row_mask:0xf bank_mask:0xf
	s_and_saveexec_b64 s[8:9], s[4:5]
	s_cbranch_execz .LBB0_683
	v_add_u32_e32 v202, 0x10018, v197
	v_add_u32_e32 v203, 0x1001c, v197
	ds_add_f32 v202, v242
	ds_add_f32 v203, v243
.LBB0_683:
	s_or_b64 exec, exec, s[8:9]
	v_exp_f32_e32 v66, v66
	v_exp_f32_e32 v67, v67
	v_exp_f32_e32 v68, v68
	v_add_u32_e32 v198, 32, v196
	v_exp_f32_e32 v69, v69
	v_mul_f32_e32 v66, v106, v66
	v_cmp_le_i32_e32 vcc, v198, v100
	v_add_u32_e32 v198, 33, v196
	v_mul_f32_e32 v67, v106, v67
	v_cndmask_b32_e32 v66, 0, v66, vcc
	v_cmp_le_i32_e32 vcc, v198, v100
	v_add_u32_e32 v198, 34, v196
	v_mul_f32_e32 v68, v106, v68
	v_cndmask_b32_e32 v67, 0, v67, vcc
	v_cmp_le_i32_e32 vcc, v198, v100
	v_add_u32_e32 v198, 35, v196
	v_mul_f32_e32 v69, v106, v69
	v_cndmask_b32_e32 v68, 0, v68, vcc
	v_cmp_le_i32_e32 vcc, v198, v100
	v_add_f32_e32 v198, v66, v67
	s_nop 0
	v_cndmask_b32_e32 v69, 0, v69, vcc
	s_waitcnt lgkmcnt(0)
	v_add_f32_e32 v199, v68, v69
	v_add_f32_e32 v198, v198, v199
	s_nop 0
	s_nop 1
	v_add_f32_dpp v240, v198, v198 quad_perm:[1,0,3,2] row_mask:0xf bank_mask:0xf
	v_add_f32_dpp v241, v69, v69 quad_perm:[1,0,3,2] row_mask:0xf bank_mask:0xf
	s_nop 1
	v_add_f32_dpp v242, v240, v240 quad_perm:[2,3,0,1] row_mask:0xf bank_mask:0xf
	v_add_f32_dpp v243, v241, v241 quad_perm:[2,3,0,1] row_mask:0xf bank_mask:0xf
	s_and_saveexec_b64 s[8:9], s[4:5]
	s_cbranch_execz .LBB0_685
	v_add_u32_e32 v202, 0x10020, v197
	v_add_u32_e32 v203, 0x10024, v197
	ds_add_f32 v202, v242
	ds_add_f32 v203, v243
.LBB0_685:
	s_or_b64 exec, exec, s[8:9]
	v_exp_f32_e32 v70, v70
	v_exp_f32_e32 v71, v71
	v_exp_f32_e32 v72, v72
	v_add_u32_e32 v198, 40, v196
	v_exp_f32_e32 v73, v73
	v_mul_f32_e32 v70, v106, v70
	v_cmp_le_i32_e32 vcc, v198, v100
	v_add_u32_e32 v198, 41, v196
	v_mul_f32_e32 v71, v106, v71
	v_cndmask_b32_e32 v70, 0, v70, vcc
	v_cmp_le_i32_e32 vcc, v198, v100
	v_add_u32_e32 v198, 42, v196
	v_mul_f32_e32 v72, v106, v72
	v_cndmask_b32_e32 v71, 0, v71, vcc
	v_cmp_le_i32_e32 vcc, v198, v100
	v_add_u32_e32 v198, 43, v196
	v_mul_f32_e32 v73, v106, v73
	v_cndmask_b32_e32 v72, 0, v72, vcc
	v_cmp_le_i32_e32 vcc, v198, v100
	v_add_f32_e32 v198, v70, v71
	s_nop 0
	v_cndmask_b32_e32 v73, 0, v73, vcc
	s_waitcnt lgkmcnt(0)
	v_add_f32_e32 v199, v72, v73
	v_add_f32_e32 v198, v198, v199
	s_nop 0
	s_nop 1
	v_add_f32_dpp v240, v198, v198 quad_perm:[1,0,3,2] row_mask:0xf bank_mask:0xf
	v_add_f32_dpp v241, v73, v73 quad_perm:[1,0,3,2] row_mask:0xf bank_mask:0xf
	s_nop 1
	v_add_f32_dpp v242, v240, v240 quad_perm:[2,3,0,1] row_mask:0xf bank_mask:0xf
	v_add_f32_dpp v243, v241, v241 quad_perm:[2,3,0,1] row_mask:0xf bank_mask:0xf
	s_and_saveexec_b64 s[8:9], s[4:5]
	s_cbranch_execz .LBB0_687
	v_add_u32_e32 v202, 0x10028, v197
	v_add_u32_e32 v203, 0x1002c, v197
	ds_add_f32 v202, v242
	ds_add_f32 v203, v243
.LBB0_687:
	s_or_b64 exec, exec, s[8:9]
	v_exp_f32_e32 v74, v74
	v_exp_f32_e32 v75, v75
	v_exp_f32_e32 v76, v76
	v_add_u32_e32 v198, 48, v196
	v_exp_f32_e32 v77, v77
	v_mul_f32_e32 v74, v106, v74
	v_cmp_le_i32_e32 vcc, v198, v100
	v_add_u32_e32 v198, 49, v196
	v_mul_f32_e32 v75, v106, v75
	v_cndmask_b32_e32 v74, 0, v74, vcc
	v_cmp_le_i32_e32 vcc, v198, v100
	v_add_u32_e32 v198, 50, v196
	v_mul_f32_e32 v76, v106, v76
	v_cndmask_b32_e32 v75, 0, v75, vcc
	v_cmp_le_i32_e32 vcc, v198, v100
	v_add_u32_e32 v198, 51, v196
	v_mul_f32_e32 v77, v106, v77
	v_cndmask_b32_e32 v76, 0, v76, vcc
	v_cmp_le_i32_e32 vcc, v198, v100
	v_add_f32_e32 v198, v74, v75
	s_nop 0
	v_cndmask_b32_e32 v77, 0, v77, vcc
	s_waitcnt lgkmcnt(0)
	v_add_f32_e32 v199, v76, v77
	v_add_f32_e32 v198, v198, v199
	s_nop 0
	s_nop 1
	v_add_f32_dpp v240, v198, v198 quad_perm:[1,0,3,2] row_mask:0xf bank_mask:0xf
	v_add_f32_dpp v241, v77, v77 quad_perm:[1,0,3,2] row_mask:0xf bank_mask:0xf
	s_nop 1
	v_add_f32_dpp v242, v240, v240 quad_perm:[2,3,0,1] row_mask:0xf bank_mask:0xf
	v_add_f32_dpp v243, v241, v241 quad_perm:[2,3,0,1] row_mask:0xf bank_mask:0xf
	s_and_saveexec_b64 s[8:9], s[4:5]
	s_cbranch_execz .LBB0_689
	v_add_u32_e32 v202, 0x10030, v197
	v_add_u32_e32 v203, 0x10034, v197
	ds_add_f32 v202, v242
	ds_add_f32 v203, v243
.LBB0_689:
	s_or_b64 exec, exec, s[8:9]
	v_exp_f32_e32 v78, v78
	v_exp_f32_e32 v79, v79
	v_exp_f32_e32 v80, v80
	v_add_u32_e32 v198, 56, v196
	v_exp_f32_e32 v81, v81
	v_mul_f32_e32 v78, v106, v78
	v_cmp_le_i32_e32 vcc, v198, v100
	v_add_u32_e32 v198, 57, v196
	v_mul_f32_e32 v79, v106, v79
	v_cndmask_b32_e32 v78, 0, v78, vcc
	v_cmp_le_i32_e32 vcc, v198, v100
	v_add_u32_e32 v198, 58, v196
	v_mul_f32_e32 v80, v106, v80
	v_cndmask_b32_e32 v79, 0, v79, vcc
	v_cmp_le_i32_e32 vcc, v198, v100
	v_add_u32_e32 v196, 59, v196
	v_mul_f32_e32 v81, v106, v81
	v_cndmask_b32_e32 v80, 0, v80, vcc
	v_cmp_le_i32_e32 vcc, v196, v100
	v_add_f32_e32 v196, v78, v79
	s_nop 0
	v_cndmask_b32_e32 v81, 0, v81, vcc
	v_add_f32_e32 v198, v80, v81
	v_add_f32_e32 v196, v196, v198
	s_waitcnt lgkmcnt(0)
	s_nop 1
	v_add_f32_dpp v240, v196, v196 quad_perm:[1,0,3,2] row_mask:0xf bank_mask:0xf
	v_add_f32_dpp v241, v81, v81 quad_perm:[1,0,3,2] row_mask:0xf bank_mask:0xf
	s_nop 1
	v_add_f32_dpp v242, v240, v240 quad_perm:[2,3,0,1] row_mask:0xf bank_mask:0xf
	v_add_f32_dpp v243, v241, v241 quad_perm:[2,3,0,1] row_mask:0xf bank_mask:0xf
	s_and_saveexec_b64 s[8:9], s[4:5]
	s_cbranch_execz .LBB0_670
	v_add_u32_e32 v201, 0x10038, v197
	v_add_u32_e32 v197, 0x1003c, v197
	ds_add_f32 v201, v242
	ds_add_f32 v197, v243
	s_branch .LBB0_670

.LBB0_696:
	v_max_u32_e32 v23, v21, v22
	v_max3_u32 v23, v23, v3, v0
	v_max3_u32 v23, v23, v9, v4
	v_max3_u32 v23, v23, v11, v8
	v_max3_u32 v23, v23, v13, v10
	v_max3_u32 v23, v23, v15, v12
	v_max3_u32 v23, v23, v17, v14
	v_max3_u32 v23, v23, v19, v16
	s_nop 1
	v_max_u32_dpp v24, v23, v23 quad_perm:[1,0,3,2] row_mask:0xf bank_mask:0xf
	s_nop 1
	v_max_u32_dpp v25, v24, v24 quad_perm:[2,3,0,1] row_mask:0xf bank_mask:0xf
	s_nop 1
	v_max_u32_dpp v23, v25, v25 row_half_mirror row_mask:0xf bank_mask:0xf
	v_cmp_ne_u32_e32 vcc, 0, v23
	s_and_saveexec_b64 s[6:7], vcc
	s_cbranch_execz .LBB0_695
	v_sub_u32_e32 v24, 0, v23
	v_and_b32_e32 v25, 0x7f, v24
	v_lshlrev_b32_e64 v26, v24, 1
	v_bfe_u32 v24, v24, 5, 2
	v_cmp_gt_u32_e32 vcc, 32, v25
	s_nop 1
	v_cndmask_b32_e32 v25, 0, v26, vcc
	v_cmp_eq_u32_e32 vcc, 2, v24
	v_or_b32_e32 v2, v25, v2
	s_nop 0
	v_cndmask_b32_e32 v25, 0, v26, vcc
	v_cmp_eq_u32_e32 vcc, 1, v24
	v_or_b32_e32 v7, v25, v7
	s_nop 0
	v_cndmask_b32_e32 v27, 0, v26, vcc
	v_cmp_eq_u32_e32 vcc, 3, v24
	v_or_b32_e32 v6, v27, v6
	s_nop 0
	v_cndmask_b32_e32 v24, 0, v26, vcc
	v_or_b32_e32 v5, v24, v5
	s_branch .LBB0_695

.LBB0_1017:
	v_mfma_f32_16x16x32_bf16 v[62:65], v[38:41], v[2:5], 0
	v_add_u32_e32 v0, 0x400, v61
	s_mov_b64 s[14:15], 0x10000
	s_add_i32 s11, s11, 16
	v_mfma_f32_16x16x32_bf16 v[66:69], v[38:41], v[6:9], 0
	v_lshl_add_u64 v[56:57], v[56:57], 0, s[14:15]
	s_and_b64 vcc, exec, s[12:13]
	v_mfma_f32_16x16x32_bf16 v[70:73], v[38:41], v[10:13], 0
	v_mfma_f32_16x16x32_bf16 v[74:77], v[38:41], v[14:17], 0
	s_nop 3
	ds_write2_b32 v61, v62, v66 offset1:16
	ds_write2_b32 v61, v63, v67 offset0:132 offset1:148
	ds_write2_b32 v0, v64, v68 offset0:8 offset1:24
	v_mfma_f32_16x16x32_bf16 v[78:81], v[38:41], v[18:21], 0
	ds_write2_b32 v0, v65, v69 offset0:140 offset1:156
	ds_write2_b32 v61, v70, v74 offset0:32 offset1:48
	ds_write2_b32 v61, v71, v75 offset0:164 offset1:180
	v_mfma_f32_16x16x32_bf16 v[62:65], v[38:41], v[22:25], 0
	ds_write2_b32 v0, v72, v76 offset0:40 offset1:56
	ds_write2_b32 v0, v73, v77 offset0:172 offset1:188
	s_nop 5
	ds_write2_b32 v61, v78, v62 offset0:64 offset1:80
	ds_write2_b32 v61, v79, v63 offset0:196 offset1:212
	ds_write2_b32 v0, v80, v64 offset0:72 offset1:88
	ds_write2_b32 v0, v81, v65 offset0:204 offset1:220
	v_mfma_f32_16x16x32_bf16 v[66:69], v[38:41], v[26:29], 0
	v_mfma_f32_16x16x32_bf16 v[38:41], v[38:41], v[30:33], 0
	s_nop 7
	ds_write2_b32 v61, v66, v38 offset0:96 offset1:112
	ds_write2_b32 v61, v67, v39 offset0:228 offset1:244
	ds_write2_b32 v0, v68, v40 offset0:104 offset1:120
	ds_write2_b32 v0, v69, v41 offset0:236 offset1:252
	ds_read_b32 v110, v60
	ds_read_b32 v111, v60 offset:256
	ds_read_b32 v112, v60 offset:528
	ds_read_b32 v113, v60 offset:784
	ds_read_b32 v114, v60 offset:1056
	ds_read_b32 v115, v60 offset:1312
	ds_read_b32 v116, v60 offset:1584
	ds_read_b32 v117, v60 offset:1840
	ds_read_b32 v118, v60 offset:2112
	ds_read_b32 v119, v60 offset:2368
	ds_read_b32 v120, v60 offset:2640
	ds_read_b32 v121, v60 offset:2896
	ds_read_b32 v122, v60 offset:3168
	ds_read_b32 v123, v60 offset:3424
	ds_read_b32 v124, v60 offset:3696
	ds_read_b32 v125, v60 offset:3952
	ds_read_b32 v126, v60 offset:4224
	ds_read_b32 v127, v60 offset:4480
	ds_read_b32 v128, v60 offset:4752
	ds_read_b32 v129, v60 offset:5008
	ds_read_b32 v130, v60 offset:5280
	ds_read_b32 v131, v60 offset:5536
	ds_read_b32 v132, v60 offset:5808
	ds_read_b32 v133, v60 offset:6064
	ds_read_b32 v134, v60 offset:6336
	ds_read_b32 v135, v60 offset:6592
	ds_read_b32 v136, v60 offset:6864
	ds_read_b32 v137, v60 offset:7120
	ds_read_b32 v138, v60 offset:7392
	ds_read_b32 v139, v60 offset:7648
	ds_read_b32 v140, v60 offset:7920
	ds_read_b32 v141, v60 offset:8176
	s_waitcnt lgkmcnt(0)
	v_fma_f32 v38, -v53, v59, v110
	v_fma_f32 v39, v53, v58, v111
	v_fma_f32 v62, v52, v58, v38
	v_fma_f32 v63, v52, v59, v39
	v_fma_f32 v38, -v53, v63, v112
	v_fma_f32 v39, v53, v62, v113
	v_fma_f32 v58, v52, v62, v38
	v_fma_f32 v59, v52, v63, v39
	v_fma_f32 v38, -v53, v59, v114
	v_fma_f32 v39, v53, v58, v115
	v_fma_f32 v62, v52, v58, v38
	v_fma_f32 v63, v52, v59, v39
	v_fma_f32 v38, -v53, v63, v116
	v_fma_f32 v39, v53, v62, v117
	v_fma_f32 v58, v52, v62, v38
	v_fma_f32 v59, v52, v63, v39
	v_fma_f32 v38, -v53, v59, v118
	v_fma_f32 v39, v53, v58, v119
	v_fma_f32 v62, v52, v58, v38
	v_fma_f32 v63, v52, v59, v39
	v_fma_f32 v38, -v53, v63, v120
	v_fma_f32 v39, v53, v62, v121
	v_fma_f32 v58, v52, v62, v38
	v_fma_f32 v59, v52, v63, v39
	v_fma_f32 v38, -v53, v59, v122
	v_fma_f32 v39, v53, v58, v123
	v_fma_f32 v62, v52, v58, v38
	v_fma_f32 v63, v52, v59, v39
	v_fma_f32 v38, -v53, v63, v124
	v_fma_f32 v39, v53, v62, v125
	v_fma_f32 v58, v52, v62, v38
	v_fma_f32 v59, v52, v63, v39
	v_fma_f32 v38, -v53, v59, v126
	v_fma_f32 v39, v53, v58, v127
	v_fma_f32 v62, v52, v58, v38
	v_fma_f32 v63, v52, v59, v39
	v_fma_f32 v38, -v53, v63, v128
	v_fma_f32 v39, v53, v62, v129
	v_fma_f32 v58, v52, v62, v38
	v_fma_f32 v59, v52, v63, v39
	v_fma_f32 v38, -v53, v59, v130
	v_fma_f32 v39, v53, v58, v131
	v_fma_f32 v62, v52, v58, v38
	v_fma_f32 v63, v52, v59, v39
	v_fma_f32 v38, -v53, v63, v132
	v_fma_f32 v39, v53, v62, v133
	v_fma_f32 v58, v52, v62, v38
	v_fma_f32 v59, v52, v63, v39
	v_fma_f32 v38, -v53, v59, v134
	v_fma_f32 v39, v53, v58, v135
	v_fma_f32 v62, v52, v58, v38
	v_fma_f32 v63, v52, v59, v39
	v_fma_f32 v38, -v53, v63, v136
	v_fma_f32 v39, v53, v62, v137
	v_fma_f32 v58, v52, v62, v38
	v_fma_f32 v59, v52, v63, v39
	v_fma_f32 v38, -v53, v59, v138
	v_fma_f32 v39, v53, v58, v139
	v_fma_f32 v62, v52, v58, v38
	v_fma_f32 v63, v52, v59, v39
	v_fma_f32 v38, -v53, v63, v140
	v_fma_f32 v39, v53, v62, v141
	v_fma_f32 v58, v52, v62, v38
	v_fma_f32 v59, v52, v63, v39
	v_mov_b32_e32 v38, v146
	v_mov_b32_e32 v39, v147
	v_mov_b32_e32 v40, v148
	v_mov_b32_e32 v41, v149
	v_mov_b64_e32 v[146:147], v[150:151]
	v_mov_b64_e32 v[148:149], v[152:153]
	v_mov_b64_e32 v[150:151], v[154:155]
	v_mov_b64_e32 v[152:153], v[156:157]
	v_mov_b64_e32 v[154:155], v[158:159]
	v_mov_b64_e32 v[156:157], v[160:161]
	s_and_b32 s14, s11, 63
	s_cmp_lg_u32 s14, 0
	s_cbranch_scc1 .Ls5a_norefill
	s_waitcnt vmcnt(0)
	v_mov_b64_e32 v[146:147], v[194:195]
	v_mov_b64_e32 v[148:149], v[196:197]
	v_mov_b64_e32 v[150:151], v[198:199]
	v_mov_b64_e32 v[152:153], v[200:201]
	v_mov_b64_e32 v[154:155], v[202:203]
	v_mov_b64_e32 v[156:157], v[204:205]
	v_mov_b64_e32 v[158:159], v[206:207]
	v_mov_b64_e32 v[160:161], v[208:209]
	s_and_saveexec_b64 s[14:15], s[4:5]
	global_load_dwordx4 v[194:197], v[210:211], off
	v_lshl_add_u64 v[210:211], v[210:211], 0, s[100:101]
	global_load_dwordx4 v[198:201], v[210:211], off
	v_lshl_add_u64 v[210:211], v[210:211], 0, s[100:101]
	global_load_dwordx4 v[202:205], v[210:211], off
	v_lshl_add_u64 v[210:211], v[210:211], 0, s[100:101]
	global_load_dwordx4 v[206:209], v[210:211], off
	v_lshl_add_u64 v[210:211], v[210:211], 0, s[100:101]
	s_or_b64 exec, exec, s[14:15]

.LBB0_1090:
	s_or_b64 exec, exec, s[16:17]
	s_mov_b64 s[100:101], 0x2000
	global_load_ushort v102, v[86:87], off
	v_lshl_add_u64 v[106:107], v[86:87], 0, s[100:101]
	global_load_ushort v103, v[106:107], off offset:-4096
	global_load_ushort v104, v[106:107], off
	v_lshl_add_u64 v[106:107], v[106:107], 0, s[100:101]
	global_load_ushort v105, v[106:107], off offset:-4096
	v_mfma_f32_16x16x32_bf16 v[94:97], v[54:57], v[2:5], 0
	v_add_u32_e32 v93, 0x400, v59
	s_mov_b64 s[22:23], 0x10000
	s_mov_b64 s[16:17], 0x8000
	v_mfma_f32_16x16x32_bf16 v[98:101], v[54:57], v[6:9], 0
	s_nop 7
	ds_write2_b32 v59, v94, v98 offset1:16
	ds_write2_b32 v59, v95, v99 offset0:132 offset1:148
	ds_write2_b32 v93, v96, v100 offset0:8 offset1:24
	ds_write2_b32 v93, v97, v101 offset0:140 offset1:156
	v_mfma_f32_16x16x32_bf16 v[94:97], v[54:57], v[10:13], 0
	s_add_i32 s20, s20, 16
	v_lshl_add_u64 v[80:81], v[80:81], 0, s[22:23]
	s_and_b64 vcc, exec, s[14:15]
	v_mfma_f32_16x16x32_bf16 v[98:101], v[54:57], v[14:17], 0
	s_nop 7
	ds_write2_b32 v59, v94, v98 offset0:32 offset1:48
	ds_write2_b32 v59, v95, v99 offset0:164 offset1:180
	ds_write2_b32 v93, v96, v100 offset0:40 offset1:56
	ds_write2_b32 v93, v97, v101 offset0:172 offset1:188
	v_mfma_f32_16x16x32_bf16 v[94:97], v[54:57], v[18:21], 0
	v_mfma_f32_16x16x32_bf16 v[98:101], v[54:57], v[22:25], 0
	s_nop 7
	ds_write2_b32 v59, v94, v98 offset0:64 offset1:80
	ds_write2_b32 v59, v95, v99 offset0:196 offset1:212
	ds_write2_b32 v93, v96, v100 offset0:72 offset1:88
	ds_write2_b32 v93, v97, v101 offset0:204 offset1:220
	v_mfma_f32_16x16x32_bf16 v[94:97], v[54:57], v[26:29], 0
	v_mfma_f32_16x16x32_bf16 v[54:57], v[54:57], v[30:33], 0
	s_nop 7
	ds_write2_b32 v59, v94, v54 offset0:96 offset1:112
	ds_write2_b32 v59, v95, v55 offset0:228 offset1:244
	ds_write2_b32 v93, v96, v56 offset0:104 offset1:120
	ds_write2_b32 v93, v97, v57 offset0:236 offset1:252
	ds_read_b32 v110, v90
	ds_read_b32 v111, v90 offset:256
	ds_read_b32 v112, v90 offset:528
	ds_read_b32 v113, v90 offset:784
	ds_read_b32 v114, v90 offset:1056
	ds_read_b32 v115, v90 offset:1312
	ds_read_b32 v116, v90 offset:1584
	ds_read_b32 v117, v90 offset:1840
	ds_read_b32 v118, v90 offset:2112
	ds_read_b32 v119, v90 offset:2368
	ds_read_b32 v120, v90 offset:2640
	ds_read_b32 v121, v90 offset:2896
	ds_read_b32 v122, v90 offset:3168
	ds_read_b32 v123, v90 offset:3424
	ds_read_b32 v124, v90 offset:3696
	ds_read_b32 v125, v90 offset:3952
	ds_read_b32 v126, v90 offset:4224
	ds_read_b32 v127, v90 offset:4480
	ds_read_b32 v128, v90 offset:4752
	ds_read_b32 v129, v90 offset:5008
	ds_read_b32 v130, v90 offset:5280
	ds_read_b32 v131, v90 offset:5536
	ds_read_b32 v132, v90 offset:5808
	ds_read_b32 v133, v90 offset:6064
	ds_read_b32 v134, v90 offset:6336
	ds_read_b32 v135, v90 offset:6592
	ds_read_b32 v136, v90 offset:6864
	ds_read_b32 v137, v90 offset:7120
	ds_read_b32 v138, v90 offset:7392
	ds_read_b32 v139, v90 offset:7648
	ds_read_b32 v140, v90 offset:7920
	ds_read_b32 v141, v90 offset:8176
	s_waitcnt lgkmcnt(0)
	v_fma_f32 v54, -v77, v89, v110
	v_fma_f32 v55, v77, v88, v111
	v_fma_f32 v56, v76, v88, v54
	v_fma_f32 v57, v76, v89, v55
	v_fma_f32 v54, -v77, v57, v112
	v_fma_f32 v55, v77, v56, v113
	v_cvt_pk_bf16_f32 v142, v56, v57
	ds_write_b16 v91, v142 offset:8448
	ds_write_b16_d16_hi v91, v142 offset:8576
	v_fma_f32 v88, v76, v56, v54
	v_fma_f32 v89, v76, v57, v55
	v_fma_f32 v54, -v77, v89, v114
	v_fma_f32 v55, v77, v88, v115
	v_cvt_pk_bf16_f32 v142, v88, v89
	ds_write_b16 v91, v142 offset:8720
	ds_write_b16_d16_hi v91, v142 offset:8848
	v_fma_f32 v56, v76, v88, v54
	v_fma_f32 v57, v76, v89, v55
	v_fma_f32 v54, -v77, v57, v116
	v_fma_f32 v55, v77, v56, v117
	v_cvt_pk_bf16_f32 v142, v56, v57
	ds_write_b16 v91, v142 offset:8992
	ds_write_b16_d16_hi v91, v142 offset:9120
	v_fma_f32 v88, v76, v56, v54
	v_fma_f32 v89, v76, v57, v55
	v_fma_f32 v54, -v77, v89, v118
	v_fma_f32 v55, v77, v88, v119
	v_cvt_pk_bf16_f32 v142, v88, v89
	ds_write_b16 v91, v142 offset:9264
	ds_write_b16_d16_hi v91, v142 offset:9392
	v_fma_f32 v56, v76, v88, v54
	v_fma_f32 v57, v76, v89, v55
	v_fma_f32 v54, -v77, v57, v120
	v_fma_f32 v55, v77, v56, v121
	v_cvt_pk_bf16_f32 v142, v56, v57
	ds_write_b16 v91, v142 offset:9536
	ds_write_b16_d16_hi v91, v142 offset:9664
	v_fma_f32 v88, v76, v56, v54
	v_fma_f32 v89, v76, v57, v55
	v_fma_f32 v54, -v77, v89, v122
	v_fma_f32 v55, v77, v88, v123
	v_cvt_pk_bf16_f32 v142, v88, v89
	ds_write_b16 v91, v142 offset:9808
	ds_write_b16_d16_hi v91, v142 offset:9936
	v_fma_f32 v56, v76, v88, v54
	v_fma_f32 v57, v76, v89, v55
	v_fma_f32 v54, -v77, v57, v124
	v_fma_f32 v55, v77, v56, v125
	v_cvt_pk_bf16_f32 v142, v56, v57
	ds_write_b16 v91, v142 offset:10080
	ds_write_b16_d16_hi v91, v142 offset:10208
	v_fma_f32 v88, v76, v56, v54
	v_fma_f32 v89, v76, v57, v55
	v_fma_f32 v54, -v77, v89, v126
	v_fma_f32 v55, v77, v88, v127
	v_cvt_pk_bf16_f32 v142, v88, v89
	ds_write_b16 v91, v142 offset:10352
	ds_write_b16_d16_hi v91, v142 offset:10480
	v_fma_f32 v56, v76, v88, v54
	v_fma_f32 v57, v76, v89, v55
	v_fma_f32 v54, -v77, v57, v128
	v_fma_f32 v55, v77, v56, v129
	v_cvt_pk_bf16_f32 v142, v56, v57
	ds_write_b16 v91, v142 offset:10624
	ds_write_b16_d16_hi v91, v142 offset:10752
	v_fma_f32 v88, v76, v56, v54
	v_fma_f32 v89, v76, v57, v55
	v_fma_f32 v54, -v77, v89, v130
	v_fma_f32 v55, v77, v88, v131
	v_cvt_pk_bf16_f32 v142, v88, v89
	ds_write_b16 v91, v142 offset:10896
	ds_write_b16_d16_hi v91, v142 offset:11024
	v_fma_f32 v56, v76, v88, v54
	v_fma_f32 v57, v76, v89, v55
	v_fma_f32 v54, -v77, v57, v132
	v_fma_f32 v55, v77, v56, v133
	v_cvt_pk_bf16_f32 v142, v56, v57
	ds_write_b16 v91, v142 offset:11168
	ds_write_b16_d16_hi v91, v142 offset:11296
	v_fma_f32 v88, v76, v56, v54
	v_fma_f32 v89, v76, v57, v55
	v_fma_f32 v54, -v77, v89, v134
	v_fma_f32 v55, v77, v88, v135
	v_cvt_pk_bf16_f32 v142, v88, v89
	ds_write_b16 v91, v142 offset:11440
	ds_write_b16_d16_hi v91, v142 offset:11568
	v_fma_f32 v56, v76, v88, v54
	v_fma_f32 v57, v76, v89, v55
	v_fma_f32 v54, -v77, v57, v136
	v_fma_f32 v55, v77, v56, v137
	v_cvt_pk_bf16_f32 v142, v56, v57
	ds_write_b16 v91, v142 offset:11712
	ds_write_b16_d16_hi v91, v142 offset:11840
	v_fma_f32 v88, v76, v56, v54
	v_fma_f32 v89, v76, v57, v55
	v_fma_f32 v54, -v77, v89, v138
	v_fma_f32 v55, v77, v88, v139
	v_cvt_pk_bf16_f32 v142, v88, v89
	ds_write_b16 v91, v142 offset:11984
	ds_write_b16_d16_hi v91, v142 offset:12112
	v_fma_f32 v56, v76, v88, v54
	v_fma_f32 v57, v76, v89, v55
	v_fma_f32 v54, -v77, v57, v140
	v_fma_f32 v55, v77, v56, v141
	v_cvt_pk_bf16_f32 v142, v56, v57
	ds_write_b16 v91, v142 offset:12256
	ds_write_b16_d16_hi v91, v142 offset:12384
	v_fma_f32 v88, v76, v56, v54
	v_fma_f32 v89, v76, v57, v55
	v_cvt_pk_bf16_f32 v142, v88, v89
	ds_write_b16 v91, v142 offset:12528
	ds_write_b16_d16_hi v91, v142 offset:12656
	ds_read_b128 v[54:57], v63 offset:8448
	ds_read_b128 v[94:97], v63 offset:8512
	s_waitcnt lgkmcnt(0)
	v_mfma_f32_16x16x32_bf16 v[54:57], v[54:57], v[34:37], 0
	v_lshl_add_u64 v[86:87], v[86:87], 0, s[22:23]
	s_waitcnt vmcnt(0)
	v_lshlrev_b32_e32 v93, 16, v102
	v_mfma_f32_16x16x32_bf16 v[54:57], v[94:97], v[38:41], v[54:57]
	ds_read_b128 v[94:97], v63 offset:8576
	s_waitcnt lgkmcnt(0)
	v_mfma_f32_16x16x32_bf16 v[54:57], v[94:97], v[42:45], v[54:57]
	ds_read_b128 v[94:97], v63 offset:8640
	s_waitcnt lgkmcnt(0)
	v_mfma_f32_16x16x32_bf16 v[54:57], v[94:97], v[46:49], v[54:57]
	v_lshlrev_b64 v[94:95], 1, v[82:83]
	v_or_b32_e32 v96, 0x1000, v94
	v_mov_b32_e32 v97, v95
	s_nop 4
	v_fma_f32 v54, v92, v93, v54
	v_mul_f32_e32 v93, 0x3d372713, v54
	v_mul_f32_e32 v93, v54, v93
	v_fma_f32 v93, v54, v93, v54
	v_mul_f32_e32 v93, 0x3f4c422a, v93
	v_add_f32_e32 v93, v93, v93
	v_mul_f32_e32 v93, 0x3fb8aa3b, v93
	v_exp_f32_e32 v93, v93
	v_lshl_add_u64 v[98:99], s[6:7], 0, v[96:97]
	v_lshl_add_u64 v[82:83], v[82:83], 0, s[16:17]
	v_add_f32_e32 v93, 1.0, v93
	v_rcp_f32_e32 v93, v93
	s_nop 0
	v_sub_f32_e32 v93, 1.0, v93
	v_mul_f32_e32 v54, v54, v93
	v_bfe_u32 v93, v54, 16, 1
	v_add3_u32 v54, v54, v93, s97
	global_store_short_d16_hi v[84:85], v54, off
	v_lshl_add_u64 v[84:85], v[84:85], 0, s[22:23]
	v_lshlrev_b32_e32 v54, 16, v103
	v_fma_f32 v54, v92, v54, v55
	v_mul_f32_e32 v55, 0x3d372713, v54
	v_mul_f32_e32 v55, v54, v55
	v_fma_f32 v55, v54, v55, v54
	v_mul_f32_e32 v55, 0x3f4c422a, v55
	v_add_f32_e32 v55, v55, v55
	v_mul_f32_e32 v55, 0x3fb8aa3b, v55
	v_exp_f32_e32 v55, v55
	s_nop 0
	v_add_f32_e32 v55, 1.0, v55
	v_rcp_f32_e32 v55, v55
	s_nop 0
	v_sub_f32_e32 v55, 1.0, v55
	v_mul_f32_e32 v54, v54, v55
	v_bfe_u32 v55, v54, 16, 1
	v_add3_u32 v93, v54, v55, s97
	v_lshl_add_u64 v[54:55], s[8:9], 0, v[96:97]
	global_store_short_d16_hi v[54:55], v93, off
	v_or_b32_e32 v54, 0x2000, v94
	v_mov_b32_e32 v55, v95
	v_lshl_add_u64 v[96:97], s[6:7], 0, v[54:55]
	v_lshl_add_u64 v[54:55], s[8:9], 0, v[54:55]
	v_or_b32_e32 v94, 0x3000, v94
	v_lshlrev_b32_e32 v93, 16, v104
	v_fma_f32 v56, v92, v93, v56
	v_mul_f32_e32 v93, 0x3d372713, v56
	v_mul_f32_e32 v93, v56, v93
	v_fma_f32 v93, v56, v93, v56
	v_mul_f32_e32 v93, 0x3f4c422a, v93
	v_add_f32_e32 v93, v93, v93
	v_mul_f32_e32 v93, 0x3fb8aa3b, v93
	v_exp_f32_e32 v93, v93
	s_nop 0
	v_add_f32_e32 v93, 1.0, v93
	v_rcp_f32_e32 v93, v93
	s_nop 0
	v_sub_f32_e32 v93, 1.0, v93
	v_mul_f32_e32 v56, v56, v93
	v_bfe_u32 v93, v56, 16, 1
	v_add3_u32 v56, v56, v93, s97
	global_store_short_d16_hi v[54:55], v56, off
	v_lshl_add_u64 v[54:55], s[6:7], 0, v[94:95]
	v_lshlrev_b32_e32 v54, 16, v105
	v_fmac_f32_e32 v57, v92, v54
	v_mul_f32_e32 v54, 0x3d372713, v57
	v_mul_f32_e32 v54, v57, v54
	v_fma_f32 v54, v57, v54, v57
	v_mul_f32_e32 v54, 0x3f4c422a, v54
	v_add_f32_e32 v54, v54, v54
	v_mul_f32_e32 v54, 0x3fb8aa3b, v54
	v_exp_f32_e32 v54, v54
	s_nop 0
	v_add_f32_e32 v54, 1.0, v54
	v_rcp_f32_e32 v54, v54
	s_nop 0
	v_sub_f32_e32 v54, 1.0, v54
	v_mul_f32_e32 v54, v57, v54
	v_bfe_u32 v55, v54, 16, 1
	v_add3_u32 v56, v54, v55, s97
	v_lshl_add_u64 v[54:55], s[8:9], 0, v[94:95]
	global_store_short_d16_hi v[54:55], v56, off
	v_mov_b32_e32 v54, v50
	v_mov_b32_e32 v55, v51
	v_mov_b32_e32 v56, v52
	v_mov_b32_e32 v57, v53
	s_cbranch_vccnz .LBB0_1066
